# attention unit epilogue: wait for LDS-DMA before the output stores, unit-end barrier no longer waits for store completion (on top of rs4_sm_v4opt)
# speedup vs baseline: 1.0318x; 1.0004x over previous
; __device__ __forceinline__ int crow(int r, int hi) { return (r & 3) + 8 * (r >> 2) + 4 * hi; }
; __device__ __forceinline__ unsigned cvtpk(float lo, float hi) { unsigned r; asm volatile("v_cvt_pk_bf16_f32 %0, %1, %2" : "=v"(r) : "v"(lo), "v"(hi)); return r; }
; #define A2_WAIT_BAR(N) asm volatile("s_waitcnt vmcnt(" #N ") lgkmcnt(0)\n\ts_barrier" ::: "memory")
; __device__ __forceinline__ int crow(int r, int hi) { return (r & 3) + 8 * (r >> 2) + 4 * hi; }
; __device__ __forceinline__ unsigned cvtpk(float lo, float hi) { unsigned r; asm volatile("v_cvt_pk_bf16_f32 %0, %1, %2" : "=v"(r) : "v"(lo), "v"(hi)); return r; }
; __device__ __forceinline__ void attn_unit256q(const bf16* __restrict__ Qb, const unsigned char* __restrict__ Kc, const unsigned char* __restrict__ Kl, const float* __restrict__ Sc, const float* __restrict__ Sl, ...
;     ...
;   if (hi == 0) wsf[32 + r32] = l_reg;
;   asm volatile("s_waitcnt lgkmcnt(0)" ::: "memory");
;   int lane2 = lane; asm volatile("" : "+v"(lane2));
;   const int r32b = lane2 & 31, hib = lane2 >> 5;
;   float rli[16];
; #pragma unroll
;   for (int r = 0; r < 16; ++r) rli[r] = __builtin_amdgcn_rcpf(wsf[32 + crow(r, hib)]);
;   bf16* Ow = Ob + (size_t)(wid * 32) * LDO + r32b;
; #pragma unroll
;   for (int r = 0; r < 16; ++r)
; #pragma unroll
;     for (int d = 0; d < 8; ++d) Ow[(size_t)crow(r, hib) * LDO + d * 32] = (bf16)(cvtpk(o[d][r] * rli[r], 0.f) & 0xffffu);
;   A2_WAIT_BAR(0);
.LBB0_528:
	s_or_b64 exec, exec, s[2:3]
	s_waitcnt vmcnt(0) lgkmcnt(0)
	s_lshl_b64 s[0:1], s[14:15], 14
	v_ashrrev_i32_e32 v3, 5, v219
	v_lshl_add_u32 v140, v3, 4, s78
	ds_read_b128 v[132:135], v140 offset:128
	ds_read_b128 v[136:139], v140 offset:160
	v_readlane_b32 s2, v243, 53
	v_readlane_b32 s3, v243, 54
	s_add_u32 s0, s2, s0
	s_addc_u32 s1, s3, s1
	s_lshl_b32 s2, s71, 13
	s_add_u32 s0, s0, s2
	s_waitcnt lgkmcnt(1)
	v_rcp_f32_e32 v141, v132
	v_rcp_f32_e32 v142, v133
	v_rcp_f32_e32 v143, v134
	v_rcp_f32_e32 v144, v135
	s_waitcnt lgkmcnt(0)
	v_rcp_f32_e32 v145, v136
	ds_read_b128 v[132:135], v140 offset:192
	v_rcp_f32_e32 v146, v137
	v_rcp_f32_e32 v147, v138
	v_rcp_f32_e32 v148, v139
	ds_read_b128 v[136:139], v140 offset:224
	s_addc_u32 s1, s1, 0
	s_lshl_b32 s2, s13, 9
	s_add_u32 s2, s0, s2
	s_addc_u32 s3, s1, 0
	s_ashr_i32 s13, s12, 31
	s_lshl_b64 s[0:1], s[12:13], 14
	s_waitcnt lgkmcnt(1)
	v_rcp_f32_e32 v140, v132
	s_waitcnt lgkmcnt(0)
	v_rcp_f32_e32 v152, v136
	v_and_b32_e32 v132, 31, v219
	s_add_u32 s0, s2, s0
	v_lshlrev_b32_e32 v136, 2, v3
	v_rcp_f32_e32 v153, v137
	s_addc_u32 s1, s3, s1
	v_lshlrev_b32_e32 v200, 1, v132
	v_ashrrev_i32_e32 v137, 31, v136
	v_rcp_f32_e32 v149, v133
	v_rcp_f32_e32 v150, v134
	v_rcp_f32_e32 v151, v135
	v_lshl_add_u64 v[134:135], s[0:1], 0, v[200:201]
	v_lshlrev_b64 v[132:133], 14, v[136:137]
	v_mul_f32_e32 v3, v4, v141
	v_lshl_add_u64 v[132:133], v[134:135], 0, v[132:133]
	v_cvt_pk_bf16_f32 v3, v3, v201
	global_store_short v[132:133], v3, off
	v_mul_f32_e32 v3, v116, v141
	v_cvt_pk_bf16_f32 v3, v3, v201
	global_store_short v[132:133], v3, off offset:64
	v_mul_f32_e32 v3, v100, v141
	v_cvt_pk_bf16_f32 v3, v3, v201
	global_store_short v[132:133], v3, off offset:128
	v_mul_f32_e32 v3, v84, v141
	v_cvt_pk_bf16_f32 v3, v3, v201
	global_store_short v[132:133], v3, off offset:192
	v_mul_f32_e32 v3, v68, v141
	v_cvt_pk_bf16_f32 v3, v3, v201
	global_store_short v[132:133], v3, off offset:256
	v_mul_f32_e32 v3, v52, v141
	v_cvt_pk_bf16_f32 v3, v3, v201
	global_store_short v[132:133], v3, off offset:320
	v_mul_f32_e32 v3, v36, v141
	v_cvt_pk_bf16_f32 v3, v3, v201
	v_rcp_f32_e32 v154, v138
	global_store_short v[132:133], v3, off offset:384
	v_mul_f32_e32 v3, v20, v141
	v_or_b32_e32 v138, 1, v136
	v_rcp_f32_e32 v155, v139
	v_cvt_pk_bf16_f32 v3, v3, v201
	v_ashrrev_i32_e32 v139, 31, v138
	global_store_short v[132:133], v3, off offset:448
	v_lshlrev_b64 v[138:139], 14, v[138:139]
	v_mul_f32_e32 v3, v5, v142
	v_lshl_add_u64 v[138:139], v[134:135], 0, v[138:139]
	v_cvt_pk_bf16_f32 v3, v3, v201
	global_store_short v[138:139], v3, off
	v_mul_f32_e32 v3, v117, v142
	v_cvt_pk_bf16_f32 v3, v3, v201
	global_store_short v[138:139], v3, off offset:64
	v_mul_f32_e32 v3, v101, v142
	v_cvt_pk_bf16_f32 v3, v3, v201
	global_store_short v[138:139], v3, off offset:128
	v_mul_f32_e32 v3, v85, v142
	v_cvt_pk_bf16_f32 v3, v3, v201
	global_store_short v[138:139], v3, off offset:192
	v_mul_f32_e32 v3, v69, v142
	v_cvt_pk_bf16_f32 v3, v3, v201
	global_store_short v[138:139], v3, off offset:256
	v_mul_f32_e32 v3, v53, v142
	v_cvt_pk_bf16_f32 v3, v3, v201
	global_store_short v[138:139], v3, off offset:320
	v_mul_f32_e32 v3, v37, v142
	v_cvt_pk_bf16_f32 v3, v3, v201
	global_store_short v[138:139], v3, off offset:384
	v_mul_f32_e32 v3, v21, v142
	v_or_b32_e32 v4, 2, v136
	v_cvt_pk_bf16_f32 v3, v3, v201
	v_ashrrev_i32_e32 v5, 31, v4
	global_store_short v[138:139], v3, off offset:448
	v_lshlrev_b64 v[4:5], 14, v[4:5]
	v_mul_f32_e32 v3, v6, v143
	v_lshl_add_u64 v[4:5], v[134:135], 0, v[4:5]
	v_cvt_pk_bf16_f32 v3, v3, v201
	global_store_short v[4:5], v3, off
	v_mul_f32_e32 v3, v118, v143
	v_cvt_pk_bf16_f32 v3, v3, v201
	global_store_short v[4:5], v3, off offset:64
	v_mul_f32_e32 v3, v102, v143
	v_cvt_pk_bf16_f32 v3, v3, v201
	global_store_short v[4:5], v3, off offset:128
	v_mul_f32_e32 v3, v86, v143
	v_cvt_pk_bf16_f32 v3, v3, v201
	global_store_short v[4:5], v3, off offset:192
	v_mul_f32_e32 v3, v70, v143
	v_cvt_pk_bf16_f32 v3, v3, v201
	global_store_short v[4:5], v3, off offset:256
	v_mul_f32_e32 v3, v54, v143
	v_cvt_pk_bf16_f32 v3, v3, v201
	global_store_short v[4:5], v3, off offset:320
	v_mul_f32_e32 v3, v38, v143
	v_cvt_pk_bf16_f32 v3, v3, v201
	global_store_short v[4:5], v3, off offset:384
	v_mul_f32_e32 v3, v22, v143
	v_cvt_pk_bf16_f32 v3, v3, v201
	global_store_short v[4:5], v3, off offset:448
	v_or_b32_e32 v4, 3, v136
	v_ashrrev_i32_e32 v5, 31, v4
	v_lshlrev_b64 v[4:5], 14, v[4:5]
	v_mul_f32_e32 v3, v7, v144
	v_lshl_add_u64 v[4:5], v[134:135], 0, v[4:5]
	v_cvt_pk_bf16_f32 v3, v3, v201
	global_store_short v[4:5], v3, off
	v_mul_f32_e32 v3, v119, v144
	v_cvt_pk_bf16_f32 v3, v3, v201
	global_store_short v[4:5], v3, off offset:64
	v_mul_f32_e32 v3, v103, v144
	v_cvt_pk_bf16_f32 v3, v3, v201
	global_store_short v[4:5], v3, off offset:128
	v_mul_f32_e32 v3, v87, v144
	v_cvt_pk_bf16_f32 v3, v3, v201
	global_store_short v[4:5], v3, off offset:192
	v_mul_f32_e32 v3, v71, v144
	v_cvt_pk_bf16_f32 v3, v3, v201
	global_store_short v[4:5], v3, off offset:256
	v_mul_f32_e32 v3, v55, v144
	v_cvt_pk_bf16_f32 v3, v3, v201
	global_store_short v[4:5], v3, off offset:320
	v_mul_f32_e32 v3, v39, v144
	v_cvt_pk_bf16_f32 v3, v3, v201
	global_store_short v[4:5], v3, off offset:384
	v_mul_f32_e32 v3, v23, v144
	s_mov_b64 s[0:1], 0x20000
	v_cvt_pk_bf16_f32 v3, v3, v201
	global_store_short v[4:5], v3, off offset:448
	v_lshl_add_u64 v[4:5], v[132:133], 0, s[0:1]
	s_mov_b32 s0, 0x20000
	v_mul_f32_e32 v3, v8, v145
	v_add_co_u32_e32 v6, vcc, s0, v132
	v_cvt_pk_bf16_f32 v3, v3, v201
	s_mov_b64 s[0:1], 0x24000
	s_nop 0
	v_addc_co_u32_e32 v7, vcc, 0, v133, vcc
; __device__ __forceinline__ int crow(int r, int hi) { return (r & 3) + 8 * (r >> 2) + 4 * hi; }
; __device__ __forceinline__ unsigned cvtpk(float lo, float hi) { unsigned r; asm volatile("v_cvt_pk_bf16_f32 %0, %1, %2" : "=v"(r) : "v"(lo), "v"(hi)); return r; }
; __device__ __forceinline__ int crow(int r, int hi) { return (r & 3) + 8 * (r >> 2) + 4 * hi; }
; __device__ __forceinline__ unsigned cvtpk(float lo, float hi) { unsigned r; asm volatile("v_cvt_pk_bf16_f32 %0, %1, %2" : "=v"(r) : "v"(lo), "v"(hi)); return r; }
; __device__ __forceinline__ void attn_unit256q(const bf16* __restrict__ Qb, const unsigned char* __restrict__ Kc, const unsigned char* __restrict__ Kl, const float* __restrict__ Sc, const float* __restrict__ Sl, ...
;     ...
;   bf16* Ow = Ob + (size_t)(wid * 32) * LDO + r32b;
; #pragma unroll
;   for (int r = 0; r < 16; ++r)
; #pragma unroll
;     for (int d = 0; d < 8; ++d) Ow[(size_t)crow(r, hib) * LDO + d * 32] = (bf16)(cvtpk(o[d][r] * rli[r], 0.f) & 0xffffu);
	global_store_short v[6:7], v3, off
	v_mul_f32_e32 v3, v120, v145
	v_cvt_pk_bf16_f32 v3, v3, v201
	global_store_short v[4:5], v3, off offset:64
	v_mul_f32_e32 v3, v104, v145
	v_cvt_pk_bf16_f32 v3, v3, v201
	global_store_short v[4:5], v3, off offset:128
	v_mul_f32_e32 v3, v88, v145
	v_cvt_pk_bf16_f32 v3, v3, v201
	global_store_short v[4:5], v3, off offset:192
	v_mul_f32_e32 v3, v72, v145
	v_cvt_pk_bf16_f32 v3, v3, v201
	global_store_short v[4:5], v3, off offset:256
	v_mul_f32_e32 v3, v56, v145
	v_cvt_pk_bf16_f32 v3, v3, v201
	global_store_short v[4:5], v3, off offset:320
	v_mul_f32_e32 v3, v40, v145
	v_cvt_pk_bf16_f32 v3, v3, v201
	global_store_short v[4:5], v3, off offset:384
	v_mul_f32_e32 v3, v24, v145
	v_cvt_pk_bf16_f32 v3, v3, v201
	global_store_short v[4:5], v3, off offset:448
	v_lshl_add_u64 v[4:5], v[132:133], 0, s[0:1]
	s_mov_b32 s0, 0x24000
	v_mul_f32_e32 v3, v9, v146
	v_add_co_u32_e32 v6, vcc, s0, v132
	v_cvt_pk_bf16_f32 v3, v3, v201
	s_mov_b64 s[0:1], 0x28000
	s_nop 0
	v_addc_co_u32_e32 v7, vcc, 0, v133, vcc
	global_store_short v[6:7], v3, off
	v_mul_f32_e32 v3, v121, v146
	v_cvt_pk_bf16_f32 v3, v3, v201
	global_store_short v[4:5], v3, off offset:64
	v_mul_f32_e32 v3, v105, v146
	v_cvt_pk_bf16_f32 v3, v3, v201
	global_store_short v[4:5], v3, off offset:128
	v_mul_f32_e32 v3, v89, v146
	v_cvt_pk_bf16_f32 v3, v3, v201
	global_store_short v[4:5], v3, off offset:192
	v_mul_f32_e32 v3, v73, v146
	v_cvt_pk_bf16_f32 v3, v3, v201
	global_store_short v[4:5], v3, off offset:256
	v_mul_f32_e32 v3, v57, v146
	v_cvt_pk_bf16_f32 v3, v3, v201
	global_store_short v[4:5], v3, off offset:320
	v_mul_f32_e32 v3, v41, v146
	v_cvt_pk_bf16_f32 v3, v3, v201
	global_store_short v[4:5], v3, off offset:384
	v_mul_f32_e32 v3, v25, v146
	v_cvt_pk_bf16_f32 v3, v3, v201
	global_store_short v[4:5], v3, off offset:448
	v_lshl_add_u64 v[4:5], v[132:133], 0, s[0:1]
	s_mov_b32 s0, 0x28000
	v_mul_f32_e32 v3, v10, v147
	v_add_co_u32_e32 v6, vcc, s0, v132
	v_cvt_pk_bf16_f32 v3, v3, v201
	s_mov_b64 s[0:1], 0x2c000
	s_nop 0
	v_addc_co_u32_e32 v7, vcc, 0, v133, vcc
	global_store_short v[6:7], v3, off
	v_mul_f32_e32 v3, v122, v147
	v_cvt_pk_bf16_f32 v3, v3, v201
	global_store_short v[4:5], v3, off offset:64
	v_mul_f32_e32 v3, v106, v147
	v_cvt_pk_bf16_f32 v3, v3, v201
	global_store_short v[4:5], v3, off offset:128
	v_mul_f32_e32 v3, v90, v147
	v_cvt_pk_bf16_f32 v3, v3, v201
	global_store_short v[4:5], v3, off offset:192
	v_mul_f32_e32 v3, v74, v147
	v_cvt_pk_bf16_f32 v3, v3, v201
	global_store_short v[4:5], v3, off offset:256
	v_mul_f32_e32 v3, v58, v147
	v_cvt_pk_bf16_f32 v3, v3, v201
	global_store_short v[4:5], v3, off offset:320
	v_mul_f32_e32 v3, v42, v147
	v_cvt_pk_bf16_f32 v3, v3, v201
	global_store_short v[4:5], v3, off offset:384
	v_mul_f32_e32 v3, v26, v147
	v_cvt_pk_bf16_f32 v3, v3, v201
	global_store_short v[4:5], v3, off offset:448
	v_lshl_add_u64 v[4:5], v[132:133], 0, s[0:1]
	s_mov_b32 s0, 0x2c000
	v_mul_f32_e32 v3, v11, v148
	v_add_co_u32_e32 v6, vcc, s0, v132
	v_cvt_pk_bf16_f32 v3, v3, v201
	s_mov_b64 s[0:1], 0x40000
	s_nop 0
	v_addc_co_u32_e32 v7, vcc, 0, v133, vcc
	global_store_short v[6:7], v3, off
	v_mul_f32_e32 v3, v123, v148
	v_cvt_pk_bf16_f32 v3, v3, v201
	global_store_short v[4:5], v3, off offset:64
	v_mul_f32_e32 v3, v107, v148
	v_cvt_pk_bf16_f32 v3, v3, v201
	global_store_short v[4:5], v3, off offset:128
	v_mul_f32_e32 v3, v91, v148
	v_cvt_pk_bf16_f32 v3, v3, v201
	global_store_short v[4:5], v3, off offset:192
	v_mul_f32_e32 v3, v75, v148
	v_cvt_pk_bf16_f32 v3, v3, v201
	global_store_short v[4:5], v3, off offset:256
	v_mul_f32_e32 v3, v59, v148
	v_cvt_pk_bf16_f32 v3, v3, v201
	global_store_short v[4:5], v3, off offset:320
	v_mul_f32_e32 v3, v43, v148
	v_cvt_pk_bf16_f32 v3, v3, v201
	global_store_short v[4:5], v3, off offset:384
	v_mul_f32_e32 v3, v27, v148
	v_cvt_pk_bf16_f32 v3, v3, v201
	global_store_short v[4:5], v3, off offset:448
	v_lshl_add_u64 v[4:5], v[132:133], 0, s[0:1]
	s_mov_b32 s0, 0x40000
	v_mul_f32_e32 v3, v12, v140
	v_add_co_u32_e32 v6, vcc, s0, v132
	v_cvt_pk_bf16_f32 v3, v3, v201
	s_mov_b64 s[0:1], 0x44000
	s_nop 0
	v_addc_co_u32_e32 v7, vcc, 0, v133, vcc
	global_store_short v[6:7], v3, off
	v_mul_f32_e32 v3, v124, v140
	v_cvt_pk_bf16_f32 v3, v3, v201
	global_store_short v[4:5], v3, off offset:64
	v_mul_f32_e32 v3, v108, v140
	v_cvt_pk_bf16_f32 v3, v3, v201
	global_store_short v[4:5], v3, off offset:128
	v_mul_f32_e32 v3, v92, v140
	v_cvt_pk_bf16_f32 v3, v3, v201
	global_store_short v[4:5], v3, off offset:192
	v_mul_f32_e32 v3, v76, v140
	v_cvt_pk_bf16_f32 v3, v3, v201
	global_store_short v[4:5], v3, off offset:256
	v_mul_f32_e32 v3, v60, v140
	v_cvt_pk_bf16_f32 v3, v3, v201
	global_store_short v[4:5], v3, off offset:320
	v_mul_f32_e32 v3, v44, v140
	v_cvt_pk_bf16_f32 v3, v3, v201
	global_store_short v[4:5], v3, off offset:384
	v_mul_f32_e32 v3, v28, v140
	v_cvt_pk_bf16_f32 v3, v3, v201
	global_store_short v[4:5], v3, off offset:448
	v_lshl_add_u64 v[4:5], v[132:133], 0, s[0:1]
	s_mov_b32 s0, 0x44000
	v_mul_f32_e32 v3, v13, v149
	v_add_co_u32_e32 v6, vcc, s0, v132
	v_cvt_pk_bf16_f32 v3, v3, v201
	s_mov_b64 s[0:1], 0x48000
	s_nop 0
	v_addc_co_u32_e32 v7, vcc, 0, v133, vcc
	global_store_short v[6:7], v3, off
	v_mul_f32_e32 v3, v125, v149
	v_cvt_pk_bf16_f32 v3, v3, v201
	global_store_short v[4:5], v3, off offset:64
	v_mul_f32_e32 v3, v109, v149
	v_cvt_pk_bf16_f32 v3, v3, v201
	global_store_short v[4:5], v3, off offset:128
	v_mul_f32_e32 v3, v93, v149
	v_cvt_pk_bf16_f32 v3, v3, v201
	global_store_short v[4:5], v3, off offset:192
	v_mul_f32_e32 v3, v77, v149
	v_cvt_pk_bf16_f32 v3, v3, v201
	global_store_short v[4:5], v3, off offset:256
; __device__ __forceinline__ int crow(int r, int hi) { return (r & 3) + 8 * (r >> 2) + 4 * hi; }
; __device__ __forceinline__ unsigned cvtpk(float lo, float hi) { unsigned r; asm volatile("v_cvt_pk_bf16_f32 %0, %1, %2" : "=v"(r) : "v"(lo), "v"(hi)); return r; }
; #define A2_WAIT_BAR(N) asm volatile("s_waitcnt vmcnt(" #N ") lgkmcnt(0)\n\ts_barrier" ::: "memory")
; __device__ __forceinline__ int crow(int r, int hi) { return (r & 3) + 8 * (r >> 2) + 4 * hi; }
; __device__ __forceinline__ unsigned cvtpk(float lo, float hi) { unsigned r; asm volatile("v_cvt_pk_bf16_f32 %0, %1, %2" : "=v"(r) : "v"(lo), "v"(hi)); return r; }
; __device__ __forceinline__ void attn_unit256q(const bf16* __restrict__ Qb, const unsigned char* __restrict__ Kc, const unsigned char* __restrict__ Kl, const float* __restrict__ Sc, const float* __restrict__ Sl, ...
;     ...
;   for (int r = 0; r < 16; ++r)
; #pragma unroll
;     for (int d = 0; d < 8; ++d) Ow[(size_t)crow(r, hib) * LDO + d * 32] = (bf16)(cvtpk(o[d][r] * rli[r], 0.f) & 0xffffu);
;   A2_WAIT_BAR(0);
	v_mul_f32_e32 v3, v61, v149
	v_cvt_pk_bf16_f32 v3, v3, v201
	global_store_short v[4:5], v3, off offset:320
	v_mul_f32_e32 v3, v45, v149
	v_cvt_pk_bf16_f32 v3, v3, v201
	global_store_short v[4:5], v3, off offset:384
	v_mul_f32_e32 v3, v29, v149
	v_cvt_pk_bf16_f32 v3, v3, v201
	global_store_short v[4:5], v3, off offset:448
	v_lshl_add_u64 v[4:5], v[132:133], 0, s[0:1]
	s_mov_b32 s0, 0x48000
	v_mul_f32_e32 v3, v14, v150
	v_add_co_u32_e32 v6, vcc, s0, v132
	v_cvt_pk_bf16_f32 v3, v3, v201
	s_mov_b64 s[0:1], 0x4c000
	s_nop 0
	v_addc_co_u32_e32 v7, vcc, 0, v133, vcc
	global_store_short v[6:7], v3, off
	v_mul_f32_e32 v3, v126, v150
	v_cvt_pk_bf16_f32 v3, v3, v201
	global_store_short v[4:5], v3, off offset:64
	v_mul_f32_e32 v3, v110, v150
	v_cvt_pk_bf16_f32 v3, v3, v201
	global_store_short v[4:5], v3, off offset:128
	v_mul_f32_e32 v3, v94, v150
	v_cvt_pk_bf16_f32 v3, v3, v201
	global_store_short v[4:5], v3, off offset:192
	v_mul_f32_e32 v3, v78, v150
	v_cvt_pk_bf16_f32 v3, v3, v201
	global_store_short v[4:5], v3, off offset:256
	v_mul_f32_e32 v3, v62, v150
	v_cvt_pk_bf16_f32 v3, v3, v201
	global_store_short v[4:5], v3, off offset:320
	v_mul_f32_e32 v3, v46, v150
	v_cvt_pk_bf16_f32 v3, v3, v201
	global_store_short v[4:5], v3, off offset:384
	v_mul_f32_e32 v3, v30, v150
	v_cvt_pk_bf16_f32 v3, v3, v201
	global_store_short v[4:5], v3, off offset:448
	v_lshl_add_u64 v[4:5], v[132:133], 0, s[0:1]
	s_mov_b32 s0, 0x4c000
	v_mul_f32_e32 v3, v15, v151
	v_add_co_u32_e32 v6, vcc, s0, v132
	v_cvt_pk_bf16_f32 v3, v3, v201
	s_mov_b64 s[0:1], 0x60000
	s_nop 0
	v_addc_co_u32_e32 v7, vcc, 0, v133, vcc
	global_store_short v[6:7], v3, off
	v_mul_f32_e32 v3, v127, v151
	v_cvt_pk_bf16_f32 v3, v3, v201
	global_store_short v[4:5], v3, off offset:64
	v_mul_f32_e32 v3, v111, v151
	v_cvt_pk_bf16_f32 v3, v3, v201
	global_store_short v[4:5], v3, off offset:128
	v_mul_f32_e32 v3, v95, v151
	v_cvt_pk_bf16_f32 v3, v3, v201
	global_store_short v[4:5], v3, off offset:192
	v_mul_f32_e32 v3, v79, v151
	v_cvt_pk_bf16_f32 v3, v3, v201
	global_store_short v[4:5], v3, off offset:256
	v_mul_f32_e32 v3, v63, v151
	v_cvt_pk_bf16_f32 v3, v3, v201
	global_store_short v[4:5], v3, off offset:320
	v_mul_f32_e32 v3, v47, v151
	v_cvt_pk_bf16_f32 v3, v3, v201
	global_store_short v[4:5], v3, off offset:384
	v_mul_f32_e32 v3, v31, v151
	v_cvt_pk_bf16_f32 v3, v3, v201
	global_store_short v[4:5], v3, off offset:448
	v_lshl_add_u64 v[4:5], v[132:133], 0, s[0:1]
	s_mov_b32 s0, 0x60000
	v_mul_f32_e32 v3, v16, v152
	v_add_co_u32_e32 v6, vcc, s0, v132
	v_cvt_pk_bf16_f32 v3, v3, v201
	s_mov_b64 s[0:1], 0x64000
	s_nop 0
	v_addc_co_u32_e32 v7, vcc, 0, v133, vcc
	global_store_short v[6:7], v3, off
	v_mul_f32_e32 v3, v128, v152
	v_cvt_pk_bf16_f32 v3, v3, v201
	global_store_short v[4:5], v3, off offset:64
	v_mul_f32_e32 v3, v112, v152
	v_cvt_pk_bf16_f32 v3, v3, v201
	global_store_short v[4:5], v3, off offset:128
	v_mul_f32_e32 v3, v96, v152
	v_cvt_pk_bf16_f32 v3, v3, v201
	global_store_short v[4:5], v3, off offset:192
	v_mul_f32_e32 v3, v80, v152
	v_cvt_pk_bf16_f32 v3, v3, v201
	global_store_short v[4:5], v3, off offset:256
	v_mul_f32_e32 v3, v64, v152
	v_cvt_pk_bf16_f32 v3, v3, v201
	global_store_short v[4:5], v3, off offset:320
	v_mul_f32_e32 v3, v48, v152
	v_cvt_pk_bf16_f32 v3, v3, v201
	global_store_short v[4:5], v3, off offset:384
	v_mul_f32_e32 v3, v32, v152
	v_cvt_pk_bf16_f32 v3, v3, v201
	global_store_short v[4:5], v3, off offset:448
	v_lshl_add_u64 v[4:5], v[132:133], 0, s[0:1]
	s_mov_b32 s0, 0x64000
	v_mul_f32_e32 v3, v17, v153
	v_add_co_u32_e32 v6, vcc, s0, v132
	v_cvt_pk_bf16_f32 v3, v3, v201
	s_mov_b64 s[0:1], 0x68000
	s_nop 0
	v_addc_co_u32_e32 v7, vcc, 0, v133, vcc
	global_store_short v[6:7], v3, off
	v_mul_f32_e32 v3, v129, v153
	v_cvt_pk_bf16_f32 v3, v3, v201
	global_store_short v[4:5], v3, off offset:64
	v_mul_f32_e32 v3, v113, v153
	v_cvt_pk_bf16_f32 v3, v3, v201
	global_store_short v[4:5], v3, off offset:128
	v_mul_f32_e32 v3, v97, v153
	v_cvt_pk_bf16_f32 v3, v3, v201
	global_store_short v[4:5], v3, off offset:192
	v_mul_f32_e32 v3, v81, v153
	v_cvt_pk_bf16_f32 v3, v3, v201
	global_store_short v[4:5], v3, off offset:256
	v_mul_f32_e32 v3, v65, v153
	v_cvt_pk_bf16_f32 v3, v3, v201
	global_store_short v[4:5], v3, off offset:320
	v_mul_f32_e32 v3, v49, v153
	v_cvt_pk_bf16_f32 v3, v3, v201
	global_store_short v[4:5], v3, off offset:384
	v_mul_f32_e32 v3, v33, v153
	v_cvt_pk_bf16_f32 v3, v3, v201
	global_store_short v[4:5], v3, off offset:448
	v_lshl_add_u64 v[4:5], v[132:133], 0, s[0:1]
	s_mov_b32 s0, 0x68000
	v_mul_f32_e32 v3, v18, v154
	v_add_co_u32_e32 v6, vcc, s0, v132
	v_cvt_pk_bf16_f32 v3, v3, v201
	s_mov_b64 s[0:1], 0x6c000
	s_nop 0
	v_addc_co_u32_e32 v7, vcc, 0, v133, vcc
	global_store_short v[6:7], v3, off
	v_mul_f32_e32 v3, v130, v154
	v_cvt_pk_bf16_f32 v3, v3, v201
	global_store_short v[4:5], v3, off offset:64
	v_mul_f32_e32 v3, v114, v154
	v_cvt_pk_bf16_f32 v3, v3, v201
	global_store_short v[4:5], v3, off offset:128
	v_mul_f32_e32 v3, v98, v154
	v_cvt_pk_bf16_f32 v3, v3, v201
	global_store_short v[4:5], v3, off offset:192
	v_mul_f32_e32 v3, v82, v154
	v_cvt_pk_bf16_f32 v3, v3, v201
	global_store_short v[4:5], v3, off offset:256
	v_mul_f32_e32 v3, v66, v154
	v_cvt_pk_bf16_f32 v3, v3, v201
	global_store_short v[4:5], v3, off offset:320
	v_mul_f32_e32 v3, v50, v154
	v_cvt_pk_bf16_f32 v3, v3, v201
	global_store_short v[4:5], v3, off offset:384
	v_mul_f32_e32 v3, v34, v154
	v_cvt_pk_bf16_f32 v3, v3, v201
	global_store_short v[4:5], v3, off offset:448
	v_lshl_add_u64 v[4:5], v[132:133], 0, s[0:1]
	s_mov_b32 s0, 0x6c000
	v_mul_f32_e32 v3, v19, v155
	v_add_co_u32_e32 v6, vcc, s0, v132
	v_cvt_pk_bf16_f32 v3, v3, v201
	s_add_i32 s35, s35, 1
	s_nop 0
	v_addc_co_u32_e32 v7, vcc, 0, v133, vcc
	global_store_short v[6:7], v3, off
	v_mul_f32_e32 v3, v131, v155
	v_cvt_pk_bf16_f32 v3, v3, v201
	global_store_short v[4:5], v3, off offset:64
	v_mul_f32_e32 v3, v115, v155
	v_cvt_pk_bf16_f32 v3, v3, v201
	global_store_short v[4:5], v3, off offset:128
	v_mul_f32_e32 v3, v99, v155
	v_cvt_pk_bf16_f32 v3, v3, v201
	global_store_short v[4:5], v3, off offset:192
	v_mul_f32_e32 v3, v83, v155
	v_cvt_pk_bf16_f32 v3, v3, v201
	global_store_short v[4:5], v3, off offset:256
	v_mul_f32_e32 v3, v67, v155
	v_cvt_pk_bf16_f32 v3, v3, v201
	global_store_short v[4:5], v3, off offset:320
	v_mul_f32_e32 v3, v51, v155
	v_cvt_pk_bf16_f32 v3, v3, v201
	global_store_short v[4:5], v3, off offset:384
	v_mul_f32_e32 v3, v35, v155
	v_cvt_pk_bf16_f32 v3, v3, v201
	global_store_short v[4:5], v3, off offset:448
	s_waitcnt lgkmcnt(0)
	s_barrier
	s_mov_b64 s[2:3], 0
